# same as previous best; residual-epilogue prefetch uses a separate address temp (no load destination overlaps its address pair)
# speedup vs baseline: 1.0033x; 1.0033x over previous
.LBB0_1042:
	v_lshl_add_u32 v142, s56, 8, v146
	v_lshl_or_b32 v138, s58, 8, v148
	v_ashrrev_i32_e32 v143, 31, v142
	v_ashrrev_i32_e32 v139, 31, v138
	v_lshlrev_b64 v[140:141], 11, v[142:143]
	v_lshl_add_u64 v[150:151], s[42:43], 0, v[140:141]
	v_lshlrev_b64 v[138:139], 1, v[138:139]
	v_lshl_add_u64 v[154:155], v[150:151], 0, v[138:139]
	global_load_dwordx4 v[150:153], v[154:155], off
	global_load_dwordx4 v[160:163], v[154:155], off offset:256
	v_add_co_u32_e32 v156, vcc, 0x8000, v154
	s_nop 1
	v_addc_co_u32_e32 v157, vcc, 0, v155, vcc
	global_load_dwordx4 v[164:167], v[156:157], off
	global_load_dwordx4 v[168:171], v[156:157], off offset:256
	v_add_co_u32_e32 v156, vcc, 0x10000, v154
	s_nop 1
	v_addc_co_u32_e32 v157, vcc, 0, v155, vcc
	global_load_dwordx4 v[172:175], v[156:157], off
	global_load_dwordx4 v[176:179], v[156:157], off offset:256
	v_add_co_u32_e32 v156, vcc, 0x18000, v154
	s_nop 1
	v_addc_co_u32_e32 v157, vcc, 0, v155, vcc
	global_load_dwordx4 v[180:183], v[156:157], off
	global_load_dwordx4 v[184:187], v[156:157], off offset:256
	v_add_co_u32_e32 v156, vcc, 0x40000, v154
	s_nop 1
	v_addc_co_u32_e32 v157, vcc, 0, v155, vcc
	global_load_dwordx4 v[188:191], v[156:157], off
	global_load_dwordx4 v[206:209], v[156:157], off offset:256
	v_add_co_u32_e32 v156, vcc, 0x48000, v154
	s_nop 1
	v_addc_co_u32_e32 v157, vcc, 0, v155, vcc
	global_load_dwordx4 v[210:213], v[156:157], off
	global_load_dwordx4 v[214:217], v[156:157], off offset:256
	v_add_co_u32_e32 v156, vcc, 0x50000, v154
	s_nop 1
	v_addc_co_u32_e32 v157, vcc, 0, v155, vcc
	global_load_dwordx4 v[218:221], v[156:157], off
	global_load_dwordx4 v[222:225], v[156:157], off offset:256
	v_add_co_u32_e32 v156, vcc, 0x58000, v154
	s_nop 1
	v_addc_co_u32_e32 v157, vcc, 0, v155, vcc
	global_load_dwordx4 v[226:229], v[156:157], off
	global_load_dwordx4 v[230:233], v[156:157], off offset:256
	s_waitcnt vmcnt(0)
	v_lshlrev_b32_e32 v156, 16, v150
	v_and_b32_e32 v157, 0xffff0000, v150
	v_lshlrev_b32_e32 v150, 16, v151
	v_and_b32_e32 v151, 0xffff0000, v151
	v_lshlrev_b32_e32 v158, 16, v152
	v_and_b32_e32 v159, 0xffff0000, v152
	v_lshlrev_b32_e32 v152, 16, v153
	v_and_b32_e32 v153, 0xffff0000, v153
	v_pk_add_f32 v[126:127], v[126:127], v[150:151]
	v_pk_add_f32 v[124:125], v[124:125], v[156:157]
	v_pk_add_f32 v[150:151], v[122:123], v[152:153]
	v_pk_add_f32 v[122:123], v[120:121], v[158:159]
	v_mul_f32_e32 v120, v125, v125
	v_mul_f32_e32 v121, v127, v127
	v_fmac_f32_e32 v120, v124, v124
	v_fmac_f32_e32 v121, v126, v126
	v_add_f32_e32 v120, v120, v121
	v_mul_f32_e32 v121, v123, v123
	v_fmac_f32_e32 v121, v122, v122
	v_add_f32_e32 v120, v121, v120
	v_mul_f32_e32 v121, v151, v151
	v_fmac_f32_e32 v121, v150, v150
	v_add_f32_e32 v152, v121, v120
	v_cvt_pk_bf16_f32 v120, v124, v125
	v_lshl_add_u64 v[124:125], s[44:45], 0, v[140:141]
	v_cvt_pk_bf16_f32 v121, v126, v127
	v_cvt_pk_bf16_f32 v122, v122, v123
	v_cvt_pk_bf16_f32 v123, v150, v151
	v_lshl_add_u64 v[124:125], v[124:125], 0, v[138:139]
	global_store_dwordx4 v[124:125], v[120:123], off
	s_nop 1
	v_mov_b64_e32 v[120:121], v[160:161]
	v_mov_b64_e32 v[122:123], v[162:163]
	v_lshlrev_b32_e32 v126, 16, v120
	v_and_b32_e32 v127, 0xffff0000, v120
	v_lshlrev_b32_e32 v120, 16, v121
	v_and_b32_e32 v121, 0xffff0000, v121
	v_lshlrev_b32_e32 v150, 16, v122
	v_and_b32_e32 v151, 0xffff0000, v122
	v_lshlrev_b32_e32 v122, 16, v123
	v_and_b32_e32 v123, 0xffff0000, v123
	v_pk_add_f32 v[118:119], v[118:119], v[120:121]
	v_pk_add_f32 v[116:117], v[116:117], v[126:127]
	v_pk_add_f32 v[120:121], v[114:115], v[122:123]
	v_pk_add_f32 v[114:115], v[112:113], v[150:151]
	v_mul_f32_e32 v112, v117, v117
	v_mul_f32_e32 v113, v119, v119
	v_fmac_f32_e32 v112, v116, v116
	v_fmac_f32_e32 v113, v118, v118
	v_add_f32_e32 v112, v112, v113
	v_mul_f32_e32 v113, v115, v115
	v_fmac_f32_e32 v113, v114, v114
	v_add_f32_e32 v112, v113, v112
	v_mul_f32_e32 v113, v121, v121
	v_fmac_f32_e32 v113, v120, v120
	v_add_f32_e32 v112, v113, v112
	v_add_f32_e32 v122, v152, v112
	v_cvt_pk_bf16_f32 v112, v116, v117
	v_cvt_pk_bf16_f32 v113, v118, v119
	v_cvt_pk_bf16_f32 v114, v114, v115
	v_cvt_pk_bf16_f32 v115, v120, v121
	global_store_dwordx4 v[124:125], v[112:115], off offset:256
	s_nop 1
	v_mbcnt_hi_u32_b32 v112, -1, v234
	v_and_b32_e32 v114, 64, v112
	v_xor_b32_e32 v113, 16, v112
	v_add_u32_e32 v115, 64, v114
	v_cmp_lt_i32_e32 vcc, v113, v115
	s_nop 1
	v_cndmask_b32_e32 v113, v112, v113, vcc
	v_lshlrev_b32_e32 v114, 2, v113
	ds_bpermute_b32 v113, v114, v122
	s_waitcnt lgkmcnt(0)
	v_add_f32_e32 v116, v122, v113
	v_xor_b32_e32 v113, 32, v112
	v_cmp_lt_i32_e32 vcc, v113, v115
	s_nop 1
	v_cndmask_b32_e32 v112, v112, v113, vcc
	v_lshlrev_b32_e32 v115, 2, v112
	ds_bpermute_b32 v117, v115, v116
	v_lshl_add_u64 v[112:113], v[142:143], 2, s[30:31]
	s_and_saveexec_b64 s[56:57], s[38:39]
	s_cbranch_execz .LBB0_1044
	s_waitcnt lgkmcnt(0)
	v_add_f32_e32 v116, v116, v117
	global_atomic_add_f32 v[112:113], v116, off

.LBB0_1232:
	v_lshl_add_u32 v140, s52, 8, v144
	v_lshl_or_b32 v138, s54, 8, v146
	v_ashrrev_i32_e32 v141, 31, v140
	v_ashrrev_i32_e32 v139, 31, v138
	v_lshlrev_b64 v[152:153], 11, v[140:141]
	v_lshl_add_u64 v[148:149], s[22:23], 0, v[152:153]
	v_lshlrev_b64 v[138:139], 1, v[138:139]
	v_lshl_add_u64 v[154:155], v[148:149], 0, v[138:139]
	global_load_dwordx4 v[148:151], v[154:155], off
	global_load_dwordx4 v[160:163], v[154:155], off offset:256
	v_add_co_u32_e32 v156, vcc, 0x8000, v154
	s_nop 1
	v_addc_co_u32_e32 v157, vcc, 0, v155, vcc
	global_load_dwordx4 v[164:167], v[156:157], off
	global_load_dwordx4 v[168:171], v[156:157], off offset:256
	v_add_co_u32_e32 v156, vcc, 0x10000, v154
	s_nop 1
	v_addc_co_u32_e32 v157, vcc, 0, v155, vcc
	global_load_dwordx4 v[172:175], v[156:157], off
	global_load_dwordx4 v[176:179], v[156:157], off offset:256
	v_add_co_u32_e32 v156, vcc, 0x18000, v154
	s_nop 1
	v_addc_co_u32_e32 v157, vcc, 0, v155, vcc
	global_load_dwordx4 v[180:183], v[156:157], off
	global_load_dwordx4 v[184:187], v[156:157], off offset:256
	v_add_co_u32_e32 v156, vcc, 0x40000, v154
	s_nop 1
	v_addc_co_u32_e32 v157, vcc, 0, v155, vcc
	global_load_dwordx4 v[188:191], v[156:157], off
	global_load_dwordx4 v[206:209], v[156:157], off offset:256
	v_add_co_u32_e32 v156, vcc, 0x48000, v154
	s_nop 1
	v_addc_co_u32_e32 v157, vcc, 0, v155, vcc
	global_load_dwordx4 v[210:213], v[156:157], off
	global_load_dwordx4 v[214:217], v[156:157], off offset:256
	v_add_co_u32_e32 v156, vcc, 0x50000, v154
	s_nop 1
	v_addc_co_u32_e32 v157, vcc, 0, v155, vcc
	global_load_dwordx4 v[218:221], v[156:157], off
	global_load_dwordx4 v[222:225], v[156:157], off offset:256
	v_add_co_u32_e32 v156, vcc, 0x58000, v154
	s_nop 1
	v_addc_co_u32_e32 v157, vcc, 0, v155, vcc
	global_load_dwordx4 v[226:229], v[156:157], off
	global_load_dwordx4 v[230:233], v[156:157], off offset:256
	s_waitcnt vmcnt(0)
	v_lshlrev_b32_e32 v156, 16, v148
	v_and_b32_e32 v157, 0xffff0000, v148
	v_lshlrev_b32_e32 v148, 16, v149
	v_and_b32_e32 v149, 0xffff0000, v149
	v_lshlrev_b32_e32 v158, 16, v150
	v_and_b32_e32 v159, 0xffff0000, v150
	v_lshlrev_b32_e32 v150, 16, v151
	v_and_b32_e32 v151, 0xffff0000, v151
	v_pk_add_f32 v[126:127], v[126:127], v[148:149]
	v_pk_add_f32 v[124:125], v[124:125], v[156:157]
	v_pk_add_f32 v[148:149], v[122:123], v[150:151]
	v_pk_add_f32 v[122:123], v[120:121], v[158:159]
	v_mul_f32_e32 v120, v125, v125
	v_mul_f32_e32 v121, v127, v127
	v_fmac_f32_e32 v120, v124, v124
	v_fmac_f32_e32 v121, v126, v126
	v_add_f32_e32 v120, v120, v121
	v_mul_f32_e32 v121, v123, v123
	v_fmac_f32_e32 v121, v122, v122
	v_add_f32_e32 v120, v121, v120
	v_mul_f32_e32 v121, v149, v149
	v_fmac_f32_e32 v121, v148, v148
	v_add_f32_e32 v150, v121, v120
	v_cvt_pk_bf16_f32 v120, v124, v125
	v_lshl_add_u64 v[124:125], s[30:31], 0, v[152:153]
	v_cvt_pk_bf16_f32 v121, v126, v127
	v_cvt_pk_bf16_f32 v122, v122, v123
	v_cvt_pk_bf16_f32 v123, v148, v149
	v_lshl_add_u64 v[124:125], v[124:125], 0, v[138:139]
	global_store_dwordx4 v[124:125], v[120:123], off
	s_nop 1
	v_mov_b64_e32 v[120:121], v[160:161]
	v_mov_b64_e32 v[122:123], v[162:163]
	v_lshlrev_b32_e32 v126, 16, v120
	v_and_b32_e32 v127, 0xffff0000, v120
	v_lshlrev_b32_e32 v120, 16, v121
	v_and_b32_e32 v121, 0xffff0000, v121
	v_lshlrev_b32_e32 v148, 16, v122
	v_and_b32_e32 v149, 0xffff0000, v122
	v_lshlrev_b32_e32 v122, 16, v123
	v_and_b32_e32 v123, 0xffff0000, v123
	v_pk_add_f32 v[118:119], v[118:119], v[120:121]
	v_pk_add_f32 v[116:117], v[116:117], v[126:127]
	v_pk_add_f32 v[120:121], v[114:115], v[122:123]
	v_pk_add_f32 v[114:115], v[112:113], v[148:149]
	v_mul_f32_e32 v112, v117, v117
	v_mul_f32_e32 v113, v119, v119
	v_fmac_f32_e32 v112, v116, v116
	v_fmac_f32_e32 v113, v118, v118
	v_add_f32_e32 v112, v112, v113
	v_mul_f32_e32 v113, v115, v115
	v_fmac_f32_e32 v113, v114, v114
	v_add_f32_e32 v112, v113, v112
	v_mul_f32_e32 v113, v121, v121
	v_fmac_f32_e32 v113, v120, v120
	v_add_f32_e32 v112, v113, v112
	v_add_f32_e32 v122, v150, v112
	v_cvt_pk_bf16_f32 v112, v116, v117
	v_cvt_pk_bf16_f32 v113, v118, v119
	v_cvt_pk_bf16_f32 v114, v114, v115
	v_cvt_pk_bf16_f32 v115, v120, v121
	global_store_dwordx4 v[124:125], v[112:115], off offset:256
	s_nop 1
	v_mbcnt_hi_u32_b32 v113, -1, v234
	v_and_b32_e32 v114, 64, v113
	v_xor_b32_e32 v112, 16, v113
	v_add_u32_e32 v115, 64, v114
	v_cmp_lt_i32_e32 vcc, v112, v115
	v_xor_b32_e32 v116, 32, v113
	s_nop 0
	v_cndmask_b32_e32 v112, v113, v112, vcc
	v_lshlrev_b32_e32 v114, 2, v112
	ds_bpermute_b32 v112, v114, v122
	v_cmp_lt_i32_e32 vcc, v116, v115
	s_waitcnt lgkmcnt(0)
	v_add_f32_e32 v112, v122, v112
	v_cndmask_b32_e32 v113, v113, v116, vcc
	v_lshlrev_b32_e32 v115, 2, v113
	ds_bpermute_b32 v113, v115, v112
	s_and_saveexec_b64 s[52:53], s[38:39]
	s_cbranch_execz .LBB0_1234
	v_lshl_add_u64 v[116:117], v[140:141], 2, s[36:37]
	s_waitcnt lgkmcnt(0)
	v_add_f32_e32 v112, v112, v113
	global_atomic_add_f32 v[116:117], v112, off
